# per-phase setprio flips deleted + one static s_setprio 1 for waves 4-7 at kernel entry, on top of combined edits
# speedup vs baseline: 1.0186x; 1.0014x over previous
; #define LAS __attribute__((address_space(3)))
; template <class T> __device__ __forceinline__ T* lnd(T* p) { asm volatile("" : "+s"(p)); return p; }
; __global__ void __launch_bounds__(512, 2) mega_fwd(Params p) {
;     extern __shared__ __attribute__((aligned(16))) unsigned char lds[];
;     cg::grid_group grid = cg::this_grid();
;     unsigned char* ws = lnd(p.ws);
;     LAS unsigned char* ldsl = (LAS unsigned char*)lds;
;     const int G = gridDim.x, bid = blockIdx.x;
;     volatile LAS unsigned* xst = (volatile LAS unsigned*)(ldsl + LDS_STAGE);
;     if (threadIdx.x < 4) xst[threadIdx.x] = 0u;
;     __syncthreads();
;     const XcdBarrier xbar = xcd_barrier_post((unsigned*)(ws + OFF_BAR), xst);
_Z8mega_fwd6Params:
	s_load_dwordx4 s[68:71], s[0:1], 0x90
	s_load_dword s22, s[0:1], 0xa0
	s_add_u32 s6, s0, 0x98
	v_and_b32_e32 v252, 0x3ff, v0
	s_addc_u32 s7, s1, 0
	s_waitcnt lgkmcnt(0)
	s_mov_b64 s[76:77], s[68:69]
	v_readfirstlane_b32 s26, v252
	s_nop 3
	s_cmp_lt_u32 s26, 0x100
	s_cbranch_scc1 .Lprio_skip
	s_setprio 1
.Lprio_skip:
	v_cmp_gt_u32_e32 vcc, 4, v252
	s_and_saveexec_b64 s[4:5], vcc
	v_lshl_add_u32 v1, v252, 2, 0
	v_add_u32_e32 v1, 0x20000, v1
	v_mov_b32_e32 v2, 0
	ds_write_b32 v1, v2
	s_or_b64 exec, exec, s[4:5]
	s_load_dwordx16 s[80:95], s[0:1], 0x0
	s_waitcnt lgkmcnt(0)
	s_barrier
	s_add_u32 s33, s76, 0xca00000
	s_getreg_b32 s3, hwreg(HW_REG_XCC_ID, 0, 4)
	s_addc_u32 s36, s77, 0
	s_and_b32 s37, s3, 15
	s_mov_b32 s11, 0
	v_cmp_eq_u32_e64 s[96:97], 0, v252
	s_and_saveexec_b64 s[4:5], s[96:97]
	s_cbranch_execz .LBB0_4
	s_lshl_b32 s3, s37, 8
	s_add_u32 s8, s33, s3
	s_addc_u32 s9, s36, 0
	v_mov_b32_e32 v1, 1
	v_mov_b64_e32 v[2:3], s[8:9]
	flat_atomic_add v[2:3], v1 offset:1024
